# write-through (sc1) on the GLA-side mix-build stores: the last bytes written before the P3->P4 grid barrier are no longer dirty in L2, so the barrier's L2 write-back is short
# speedup vs baseline: 1.0063x; 1.0063x over previous
.LBB0_311:
	s_nop 0
	v_lshl_add_u64 v[10:11], s[34:35], 0, v[52:53]
	v_add_co_u32_e32 v60, vcc, 0x27000000, v10
	v_lshl_add_u64 v[74:75], s[34:35], 0, v[54:55]
	s_nop 0
	v_addc_co_u32_e32 v61, vcc, 0, v11, vcc
	v_add_co_u32_e32 v72, vcc, 0x2b000000, v10
	global_load_dwordx4 v[46:49], v[60:61], off nt
	s_nop 0
	v_addc_co_u32_e32 v73, vcc, 0, v11, vcc
	global_load_dwordx4 v[56:59], v[72:73], off nt
	global_load_dwordx4 v[68:71], v[74:75], off offset:-256 nt
	global_load_dwordx4 v[42:45], v[60:61], off offset:1024 nt
	global_load_dwordx4 v[38:41], v[72:73], off offset:1024 nt
	global_load_dwordx4 v[34:37], v[74:75], off offset:-128 nt
	global_load_dwordx4 v[30:33], v[60:61], off offset:2048 nt
	global_load_dwordx4 v[26:29], v[72:73], off offset:2048 nt
	global_load_dwordx4 v[22:25], v[74:75], off nt
	global_load_dwordx4 v[18:21], v[60:61], off offset:3072 nt
	global_load_dwordx4 v[14:17], v[72:73], off offset:3072 nt
	global_load_dwordx4 v[10:13], v[74:75], off offset:128 nt
	s_add_i32 s4, s4, s6
	v_lshl_add_u64 v[52:53], v[52:53], 0, s[10:11]
	v_lshl_add_u64 v[54:55], v[54:55], 0, s[12:13]
	s_cmp_lt_i32 s4, 0x10000
	s_waitcnt vmcnt(9)
	v_lshlrev_b32_e32 v67, 16, v70
	v_and_b32_e32 v70, 0xffff0000, v70
	v_lshlrev_b32_e32 v60, 16, v49
	v_and_b32_e32 v61, 0xffff0000, v49
	v_lshlrev_b32_e32 v72, 16, v59
	v_and_b32_e32 v73, 0xffff0000, v59
	v_pk_add_f32 v[60:61], v[60:61], v[72:73]
	v_lshlrev_b32_e32 v72, 16, v48
	v_and_b32_e32 v73, 0xffff0000, v48
	v_lshlrev_b32_e32 v48, 16, v58
	v_and_b32_e32 v49, 0xffff0000, v58
	v_pk_add_f32 v[48:49], v[72:73], v[48:49]
	v_mov_b32_e32 v58, v60
	v_mov_b32_e32 v59, v48
	v_pk_mul_f32 v[58:59], v[58:59], v[58:59]
	v_mov_b32_e32 v72, v61
	v_mov_b32_e32 v73, v49
	v_pk_fma_f32 v[58:59], v[72:73], v[72:73], v[58:59]
	v_mul_f32_e32 v72, 0xbfb8aa3b, v67
	v_mul_f32_e32 v73, 0xbfb8aa3b, v70
	v_exp_f32_e32 v72, v72
	v_exp_f32_e32 v73, v73
	s_nop 0
	v_pk_add_f32 v[72:73], v[72:73], 1.0 op_sel_hi:[1,0]
	s_nop 0
	s_nop 0
	v_rcp_f32_e32 v74, v73
	s_nop 0
	v_mul_f32_e32 v73, v70, v74
	s_nop 0
	v_lshlrev_b32_e32 v74, 16, v47
	v_and_b32_e32 v75, 0xffff0000, v47
	v_lshlrev_b32_e32 v47, 16, v69
	v_rcp_f32_e32 v70, v72
	s_nop 0
	v_mul_f32_e32 v72, v67, v70
	v_lshlrev_b32_e32 v76, 16, v57
	v_and_b32_e32 v77, 0xffff0000, v57
	v_and_b32_e32 v57, 0xffff0000, v69
	v_mul_f32_e32 v67, 0xbfb8aa3b, v47
	v_pk_add_f32 v[74:75], v[74:75], v[76:77]
	v_exp_f32_e32 v76, v67
	v_mul_f32_e32 v67, 0xbfb8aa3b, v57
	v_exp_f32_e32 v77, v67
	s_nop 0
	v_pk_add_f32 v[76:77], v[76:77], 1.0 op_sel_hi:[1,0]
	s_nop 0
	s_nop 0
	v_rcp_f32_e32 v67, v77
	s_nop 0
	v_mul_f32_e32 v77, v57, v67
	v_and_b32_e32 v79, 0xffff0000, v46
	v_rcp_f32_e32 v57, v76
	s_nop 0
	v_mul_f32_e32 v76, v47, v57
	v_lshlrev_b32_e32 v78, 16, v46
	v_lshlrev_b32_e32 v46, 16, v56
	v_and_b32_e32 v47, 0xffff0000, v56
	v_pk_add_f32 v[46:47], v[78:79], v[46:47]
	v_mov_b32_e32 v57, v74
	v_mov_b32_e32 v56, v46
	v_pk_mul_f32 v[56:57], v[56:57], v[56:57]
	v_mov_b32_e32 v78, v47
	v_mov_b32_e32 v79, v75
	v_lshlrev_b32_e32 v67, 16, v68
	v_and_b32_e32 v70, 0xffff0000, v68
	v_pk_fma_f32 v[56:57], v[78:79], v[78:79], v[56:57]
	v_mul_f32_e32 v68, 0xbfb8aa3b, v67
	v_mul_f32_e32 v69, 0xbfb8aa3b, v70
	v_exp_f32_e32 v68, v68
	v_exp_f32_e32 v69, v69
	v_add_f32_e32 v56, v56, v57
	v_add_f32_e32 v56, v59, v56
	v_add_f32_e32 v56, v58, v56
	v_pk_add_f32 v[68:69], v[68:69], 1.0 op_sel_hi:[1,0]
	s_waitcnt lgkmcnt(0)
	s_nop 1
	v_add_f32_dpp v56, v56, v56 quad_perm:[1,0,3,2] row_mask:0xf bank_mask:0xf
	s_waitcnt lgkmcnt(0)
	s_nop 1
	v_add_f32_dpp v56, v56, v56 quad_perm:[2,3,0,1] row_mask:0xf bank_mask:0xf
	v_rcp_f32_e32 v78, v69
	s_nop 0
	v_mul_f32_e32 v69, v70, v78
	s_waitcnt lgkmcnt(0)
	s_nop 1
	v_add_f32_dpp v56, v56, v56 row_half_mirror row_mask:0xf bank_mask:0xf
	s_waitcnt lgkmcnt(0)
	s_nop 1
	v_add_f32_dpp v56, v56, v56 row_mirror row_mask:0xf bank_mask:0xf
	v_fmamk_f32 v56, v56, 0x3c000000, v65
	v_cmp_gt_f32_e32 vcc, s5, v56
	v_mul_f32_e32 v57, 0x4f800000, v56
	v_rcp_f32_e32 v70, v68
	s_nop 0
	v_mul_f32_e32 v68, v67, v70
	v_cndmask_b32_e32 v56, v56, v57, vcc
	v_sqrt_f32_e32 v57, v56
	s_nop 0
	v_add_u32_e32 v58, -1, v57
	v_fma_f32 v59, -v58, v57, v56
	v_cmp_ge_f32_e64 s[0:1], 0, v59
	v_add_u32_e32 v59, 1, v57
	s_nop 0
	v_cndmask_b32_e64 v58, v57, v58, s[0:1]
	v_fma_f32 v57, -v59, v57, v56
	v_cmp_lt_f32_e64 s[0:1], 0, v57
	s_nop 1
	v_cndmask_b32_e64 v57, v58, v59, s[0:1]
	v_mul_f32_e32 v58, 0x37800000, v57
	v_cndmask_b32_e32 v57, v57, v58, vcc
	v_cmp_class_f32_e32 vcc, v56, v66
	s_nop 1
	v_cndmask_b32_e32 v56, v57, v56, vcc
	s_nop 0
	v_rcp_f32_e32 v56, v56
	s_nop 0
	v_pk_mul_f32 v[48:49], v[48:49], v[56:57] op_sel_hi:[1,0]
	v_pk_mul_f32 v[46:47], v[46:47], v[56:57] op_sel_hi:[1,0]
	v_pk_mul_f32 v[58:59], v[74:75], v[56:57] op_sel_hi:[1,0]
	v_pk_mul_f32 v[48:49], v[6:7], v[48:49]
	v_pk_mul_f32 v[46:47], v[2:3], v[46:47]
	v_pk_mul_f32 v[58:59], v[4:5], v[58:59]
	v_pk_mul_f32 v[48:49], v[72:73], v[48:49]
	v_pk_mul_f32 v[46:47], v[68:69], v[46:47]
	v_pk_mul_f32 v[58:59], v[76:77], v[58:59]
	v_cvt_pk_bf16_f32 v48, v48, v49
	v_lshlrev_b32_e32 v49, 16, v71
	v_and_b32_e32 v67, 0xffff0000, v71
	v_cvt_pk_bf16_f32 v46, v46, v47
	v_cvt_pk_bf16_f32 v47, v58, v59
	v_mul_f32_e32 v57, 0xbfb8aa3b, v49
	v_mul_f32_e32 v59, 0xbfb8aa3b, v67
	v_exp_f32_e32 v58, v57
	v_exp_f32_e32 v59, v59
	v_pk_mul_f32 v[56:57], v[60:61], v[56:57] op_sel_hi:[1,0]
	v_pk_add_f32 v[58:59], v[58:59], 1.0 op_sel_hi:[1,0]
	s_nop 0
	v_pk_mul_f32 v[56:57], v[8:9], v[56:57]
	v_rcp_f32_e32 v60, v59
	s_nop 0
	v_mul_f32_e32 v59, v67, v60
	s_nop 0
	v_rcp_f32_e32 v60, v58
	s_nop 0
	v_mul_f32_e32 v58, v49, v60
	v_pk_mul_f32 v[56:57], v[58:59], v[56:57]
	s_waitcnt vmcnt(6)
	v_lshlrev_b32_e32 v60, 16, v36
	v_cvt_pk_bf16_f32 v49, v56, v57
	v_lshl_add_u64 v[56:57], s[34:35], 0, v[50:51]
	v_add_co_u32_e32 v58, vcc, s7, v56
	v_and_b32_e32 v36, 0xffff0000, v36
	s_nop 0
	v_addc_co_u32_e32 v59, vcc, 0, v57, vcc
	v_add_co_u32_e32 v56, vcc, s14, v56
	v_lshl_add_u64 v[50:51], v[50:51], 0, s[8:9]
	s_nop 0
	v_addc_co_u32_e32 v57, vcc, 0, v57, vcc
	global_store_dwordx4 v[56:57], v[46:49], off offset:-4096 sc1
	s_nop 1
	v_lshlrev_b32_e32 v46, 16, v45
	v_and_b32_e32 v47, 0xffff0000, v45
	v_lshlrev_b32_e32 v48, 16, v41
	v_and_b32_e32 v49, 0xffff0000, v41
	v_pk_add_f32 v[46:47], v[46:47], v[48:49]
	v_lshlrev_b32_e32 v48, 16, v44
	v_and_b32_e32 v49, 0xffff0000, v44
	v_lshlrev_b32_e32 v44, 16, v40
	v_and_b32_e32 v45, 0xffff0000, v40
	v_pk_add_f32 v[40:41], v[48:49], v[44:45]
	v_mov_b32_e32 v44, v46
	v_mov_b32_e32 v45, v40
	v_pk_mul_f32 v[44:45], v[44:45], v[44:45]
	v_mov_b32_e32 v48, v47
	v_mov_b32_e32 v49, v41
	v_pk_fma_f32 v[44:45], v[48:49], v[48:49], v[44:45]
	v_mul_f32_e32 v48, 0xbfb8aa3b, v60
	v_mul_f32_e32 v49, 0xbfb8aa3b, v36
	v_exp_f32_e32 v48, v48
	v_exp_f32_e32 v49, v49
	s_nop 0
	v_pk_add_f32 v[48:49], v[48:49], 1.0 op_sel_hi:[1,0]
	s_nop 0
	s_nop 0
	v_rcp_f32_e32 v61, v49
	s_nop 0
	v_mul_f32_e32 v49, v36, v61
	s_nop 0
	v_rcp_f32_e32 v36, v48
	s_nop 0
	v_mul_f32_e32 v48, v60, v36
	v_lshlrev_b32_e32 v36, 16, v35
	v_lshlrev_b32_e32 v60, 16, v43
	v_and_b32_e32 v61, 0xffff0000, v43
	v_lshlrev_b32_e32 v68, 16, v39
	v_and_b32_e32 v69, 0xffff0000, v39
	v_and_b32_e32 v35, 0xffff0000, v35
	v_mul_f32_e32 v39, 0xbfb8aa3b, v36
	v_pk_add_f32 v[60:61], v[60:61], v[68:69]
	v_exp_f32_e32 v68, v39
	v_mul_f32_e32 v39, 0xbfb8aa3b, v35
	v_exp_f32_e32 v69, v39
	s_nop 0
	v_pk_add_f32 v[68:69], v[68:69], 1.0 op_sel_hi:[1,0]
	s_nop 0
	s_nop 0
	v_rcp_f32_e32 v39, v69
	s_nop 0
	v_mul_f32_e32 v69, v35, v39
	v_and_b32_e32 v71, 0xffff0000, v42
	v_rcp_f32_e32 v35, v68
	s_nop 0
	v_mul_f32_e32 v68, v36, v35
	v_lshlrev_b32_e32 v36, 16, v34
	v_and_b32_e32 v67, 0xffff0000, v34
	v_mul_f32_e32 v34, 0xbfb8aa3b, v36
	v_mul_f32_e32 v35, 0xbfb8aa3b, v67
	v_exp_f32_e32 v34, v34
	v_exp_f32_e32 v35, v35
	v_lshlrev_b32_e32 v70, 16, v42
	v_lshlrev_b32_e32 v42, 16, v38
	v_and_b32_e32 v43, 0xffff0000, v38
	v_pk_add_f32 v[42:43], v[70:71], v[42:43]
	v_mov_b32_e32 v39, v60
	v_mov_b32_e32 v38, v42
	v_pk_mul_f32 v[38:39], v[38:39], v[38:39]
	v_mov_b32_e32 v70, v43
	v_mov_b32_e32 v71, v61
	v_pk_add_f32 v[34:35], v[34:35], 1.0 op_sel_hi:[1,0]
	v_pk_fma_f32 v[38:39], v[70:71], v[70:71], v[38:39]
	s_nop 0
	v_rcp_f32_e32 v70, v35
	s_nop 0
	v_mul_f32_e32 v35, v67, v70
	s_nop 0
	v_rcp_f32_e32 v67, v34
	s_nop 0
	v_mul_f32_e32 v34, v36, v67
	v_add_f32_e32 v36, v38, v39
	v_add_f32_e32 v36, v45, v36
	v_add_f32_e32 v36, v44, v36
	s_waitcnt lgkmcnt(0)
	s_nop 1
	v_add_f32_dpp v36, v36, v36 quad_perm:[1,0,3,2] row_mask:0xf bank_mask:0xf
	s_waitcnt lgkmcnt(0)
	s_nop 1
	v_add_f32_dpp v36, v36, v36 quad_perm:[2,3,0,1] row_mask:0xf bank_mask:0xf
	s_waitcnt lgkmcnt(0)
	s_nop 1
	v_add_f32_dpp v36, v36, v36 row_half_mirror row_mask:0xf bank_mask:0xf
	s_waitcnt lgkmcnt(0)
	s_nop 1
	v_add_f32_dpp v36, v36, v36 row_mirror row_mask:0xf bank_mask:0xf
	v_fmamk_f32 v36, v36, 0x3c000000, v65
	v_cmp_gt_f32_e32 vcc, s5, v36
	v_mul_f32_e32 v38, 0x4f800000, v36
	s_nop 0
	v_cndmask_b32_e32 v36, v36, v38, vcc
	v_sqrt_f32_e32 v38, v36
	s_nop 0
	v_add_u32_e32 v39, -1, v38
	v_fma_f32 v44, -v39, v38, v36
	v_cmp_ge_f32_e64 s[0:1], 0, v44
	v_add_u32_e32 v44, 1, v38
	s_nop 0
	v_cndmask_b32_e64 v39, v38, v39, s[0:1]
	v_fma_f32 v38, -v44, v38, v36
	v_cmp_lt_f32_e64 s[0:1], 0, v38
	s_nop 1
	v_cndmask_b32_e64 v38, v39, v44, s[0:1]
	v_mul_f32_e32 v39, 0x37800000, v38
	v_cndmask_b32_e32 v38, v38, v39, vcc
	v_cmp_class_f32_e32 vcc, v36, v66
	s_nop 1
	v_cndmask_b32_e32 v36, v38, v36, vcc
	s_nop 0
	v_rcp_f32_e32 v38, v36
	s_nop 0
	v_pk_mul_f32 v[42:43], v[42:43], v[38:39] op_sel_hi:[1,0]
	v_pk_mul_f32 v[40:41], v[40:41], v[38:39] op_sel_hi:[1,0]
	v_pk_mul_f32 v[42:43], v[2:3], v[42:43]
	v_pk_mul_f32 v[40:41], v[6:7], v[40:41]
	v_pk_mul_f32 v[34:35], v[34:35], v[42:43]
	v_pk_mul_f32 v[42:43], v[60:61], v[38:39] op_sel_hi:[1,0]
	v_cvt_pk_bf16_f32 v34, v34, v35
	v_pk_mul_f32 v[42:43], v[4:5], v[42:43]
	v_pk_mul_f32 v[40:41], v[48:49], v[40:41]
	v_pk_mul_f32 v[42:43], v[68:69], v[42:43]
	v_cvt_pk_bf16_f32 v36, v40, v41
	v_cvt_pk_bf16_f32 v35, v42, v43
	v_lshlrev_b32_e32 v42, 16, v37
	v_and_b32_e32 v37, 0xffff0000, v37
	v_mul_f32_e32 v39, 0xbfb8aa3b, v42
	v_mul_f32_e32 v41, 0xbfb8aa3b, v37
	v_exp_f32_e32 v40, v39
	v_exp_f32_e32 v41, v41
	v_pk_mul_f32 v[38:39], v[46:47], v[38:39] op_sel_hi:[1,0]
	v_pk_add_f32 v[40:41], v[40:41], 1.0 op_sel_hi:[1,0]
	s_nop 0
	v_pk_mul_f32 v[38:39], v[8:9], v[38:39]
	v_rcp_f32_e32 v43, v41
	s_nop 0
	v_mul_f32_e32 v41, v37, v43
	s_nop 0
	v_rcp_f32_e32 v37, v40
	s_nop 0
	v_mul_f32_e32 v40, v42, v37
	v_pk_mul_f32 v[38:39], v[40:41], v[38:39]
	s_nop 0
	v_cvt_pk_bf16_f32 v37, v38, v39
	global_store_dwordx4 v[58:59], v[34:37], off offset:2048 sc1
	s_waitcnt vmcnt(5)
	v_lshlrev_b32_e32 v38, 16, v24
	v_and_b32_e32 v24, 0xffff0000, v24
	v_lshlrev_b32_e32 v34, 16, v33
	v_and_b32_e32 v35, 0xffff0000, v33
	v_lshlrev_b32_e32 v36, 16, v29
	v_and_b32_e32 v37, 0xffff0000, v29
	v_pk_add_f32 v[34:35], v[34:35], v[36:37]
	v_lshlrev_b32_e32 v36, 16, v32
	v_and_b32_e32 v37, 0xffff0000, v32
	v_lshlrev_b32_e32 v32, 16, v28
	v_and_b32_e32 v33, 0xffff0000, v28
	v_pk_add_f32 v[28:29], v[36:37], v[32:33]
	v_mov_b32_e32 v32, v34
	v_mov_b32_e32 v33, v28
	v_pk_mul_f32 v[32:33], v[32:33], v[32:33]
	v_mov_b32_e32 v36, v35
	v_mov_b32_e32 v37, v29
	v_pk_fma_f32 v[32:33], v[36:37], v[36:37], v[32:33]
	v_mul_f32_e32 v36, 0xbfb8aa3b, v38
	v_mul_f32_e32 v37, 0xbfb8aa3b, v24
	v_exp_f32_e32 v36, v36
	v_exp_f32_e32 v37, v37
	s_nop 0
	v_pk_add_f32 v[36:37], v[36:37], 1.0 op_sel_hi:[1,0]
	s_nop 0
	s_nop 0
	v_rcp_f32_e32 v39, v37
	s_nop 0
	v_mul_f32_e32 v37, v24, v39
	s_nop 0
	v_rcp_f32_e32 v24, v36
	s_nop 0
	v_mul_f32_e32 v36, v38, v24
	v_lshlrev_b32_e32 v24, 16, v23
	v_lshlrev_b32_e32 v38, 16, v31
	v_and_b32_e32 v39, 0xffff0000, v31
	v_lshlrev_b32_e32 v40, 16, v27
	v_and_b32_e32 v41, 0xffff0000, v27
	v_and_b32_e32 v23, 0xffff0000, v23
	v_mul_f32_e32 v27, 0xbfb8aa3b, v24
	v_pk_add_f32 v[38:39], v[38:39], v[40:41]
	v_exp_f32_e32 v40, v27
	v_mul_f32_e32 v27, 0xbfb8aa3b, v23
	v_exp_f32_e32 v41, v27
	s_nop 0
	v_pk_add_f32 v[40:41], v[40:41], 1.0 op_sel_hi:[1,0]
	s_nop 0
	s_nop 0
	v_rcp_f32_e32 v27, v41
	s_nop 0
	v_mul_f32_e32 v41, v23, v27
	s_nop 0
	v_lshlrev_b32_e32 v42, 16, v30
	v_and_b32_e32 v43, 0xffff0000, v30
	v_lshlrev_b32_e32 v30, 16, v26
	v_and_b32_e32 v31, 0xffff0000, v26
	v_pk_add_f32 v[30:31], v[42:43], v[30:31]
	v_mov_b32_e32 v27, v38
	v_mov_b32_e32 v26, v30
	v_pk_mul_f32 v[26:27], v[26:27], v[26:27]
	v_mov_b32_e32 v42, v31
	v_mov_b32_e32 v43, v39
	v_rcp_f32_e32 v23, v40
	s_nop 0
	v_mul_f32_e32 v40, v24, v23
	v_pk_fma_f32 v[26:27], v[42:43], v[42:43], v[26:27]
	v_lshlrev_b32_e32 v24, 16, v22
	v_and_b32_e32 v42, 0xffff0000, v22
	v_mul_f32_e32 v22, 0xbfb8aa3b, v24
	v_mul_f32_e32 v23, 0xbfb8aa3b, v42
	v_exp_f32_e32 v22, v22
	v_exp_f32_e32 v23, v23
	s_nop 0
	v_pk_add_f32 v[22:23], v[22:23], 1.0 op_sel_hi:[1,0]
	s_nop 0
	s_nop 0
	v_rcp_f32_e32 v43, v23
	s_nop 0
	v_mul_f32_e32 v23, v42, v43
	s_nop 0
	v_rcp_f32_e32 v42, v22
	s_nop 0
	v_mul_f32_e32 v22, v24, v42
	v_add_f32_e32 v24, v26, v27
	v_add_f32_e32 v24, v33, v24
	v_add_f32_e32 v24, v32, v24
	s_waitcnt lgkmcnt(0)
	s_nop 1
	v_add_f32_dpp v24, v24, v24 quad_perm:[1,0,3,2] row_mask:0xf bank_mask:0xf
	s_waitcnt lgkmcnt(0)
	s_nop 1
	v_add_f32_dpp v24, v24, v24 quad_perm:[2,3,0,1] row_mask:0xf bank_mask:0xf
	s_waitcnt lgkmcnt(0)
	s_nop 1
	v_add_f32_dpp v24, v24, v24 row_half_mirror row_mask:0xf bank_mask:0xf
	s_waitcnt lgkmcnt(0)
	s_nop 1
	v_add_f32_dpp v24, v24, v24 row_mirror row_mask:0xf bank_mask:0xf
	v_fmamk_f32 v24, v24, 0x3c000000, v65
	v_cmp_gt_f32_e32 vcc, s5, v24
	v_mul_f32_e32 v26, 0x4f800000, v24
	s_nop 0
	v_cndmask_b32_e32 v24, v24, v26, vcc
	v_sqrt_f32_e32 v26, v24
	s_nop 0
	v_add_u32_e32 v27, -1, v26
	v_fma_f32 v32, -v27, v26, v24
	v_cmp_ge_f32_e64 s[0:1], 0, v32
	v_add_u32_e32 v32, 1, v26
	s_nop 0
	v_cndmask_b32_e64 v27, v26, v27, s[0:1]
	v_fma_f32 v26, -v32, v26, v24
	v_cmp_lt_f32_e64 s[0:1], 0, v26
	s_nop 1
	v_cndmask_b32_e64 v26, v27, v32, s[0:1]
	v_mul_f32_e32 v27, 0x37800000, v26
	v_cndmask_b32_e32 v26, v26, v27, vcc
	v_cmp_class_f32_e32 vcc, v24, v66
	s_nop 1
	v_cndmask_b32_e32 v24, v26, v24, vcc
	s_nop 0
	v_rcp_f32_e32 v26, v24
	s_nop 0
	v_pk_mul_f32 v[30:31], v[30:31], v[26:27] op_sel_hi:[1,0]
	v_pk_mul_f32 v[28:29], v[28:29], v[26:27] op_sel_hi:[1,0]
	v_pk_mul_f32 v[30:31], v[2:3], v[30:31]
	v_pk_mul_f32 v[28:29], v[6:7], v[28:29]
	v_pk_mul_f32 v[22:23], v[22:23], v[30:31]
	v_pk_mul_f32 v[30:31], v[38:39], v[26:27] op_sel_hi:[1,0]
	v_cvt_pk_bf16_f32 v22, v22, v23
	v_pk_mul_f32 v[30:31], v[4:5], v[30:31]
	v_pk_mul_f32 v[28:29], v[36:37], v[28:29]
	v_pk_mul_f32 v[30:31], v[40:41], v[30:31]
	v_cvt_pk_bf16_f32 v24, v28, v29
	v_cvt_pk_bf16_f32 v23, v30, v31
	v_lshlrev_b32_e32 v30, 16, v25
	v_and_b32_e32 v25, 0xffff0000, v25
	v_mul_f32_e32 v27, 0xbfb8aa3b, v30
	v_mul_f32_e32 v29, 0xbfb8aa3b, v25
	v_exp_f32_e32 v28, v27
	v_exp_f32_e32 v29, v29
	v_pk_mul_f32 v[26:27], v[34:35], v[26:27] op_sel_hi:[1,0]
	v_pk_add_f32 v[28:29], v[28:29], 1.0 op_sel_hi:[1,0]
	s_nop 0
	v_pk_mul_f32 v[26:27], v[8:9], v[26:27]
	v_rcp_f32_e32 v31, v29
	s_nop 0
	v_mul_f32_e32 v29, v25, v31
	s_nop 0
	v_rcp_f32_e32 v25, v28
	s_nop 0
	v_mul_f32_e32 v28, v30, v25
	v_pk_mul_f32 v[26:27], v[28:29], v[26:27]
	s_nop 0
	v_cvt_pk_bf16_f32 v25, v26, v27
	global_store_dwordx4 v[56:57], v[22:25], off sc1
	s_waitcnt vmcnt(3)
	v_lshlrev_b32_e32 v26, 16, v12
	v_and_b32_e32 v12, 0xffff0000, v12
	v_lshlrev_b32_e32 v22, 16, v21
	v_and_b32_e32 v23, 0xffff0000, v21
	v_lshlrev_b32_e32 v24, 16, v17
	v_and_b32_e32 v25, 0xffff0000, v17
	v_pk_add_f32 v[22:23], v[22:23], v[24:25]
	v_lshlrev_b32_e32 v24, 16, v20
	v_and_b32_e32 v25, 0xffff0000, v20
	v_lshlrev_b32_e32 v20, 16, v16
	v_and_b32_e32 v21, 0xffff0000, v16
	v_pk_add_f32 v[16:17], v[24:25], v[20:21]
	v_mov_b32_e32 v20, v22
	v_mov_b32_e32 v21, v16
	v_pk_mul_f32 v[20:21], v[20:21], v[20:21]
	v_mov_b32_e32 v24, v23
	v_mov_b32_e32 v25, v17
	v_pk_fma_f32 v[20:21], v[24:25], v[24:25], v[20:21]
	v_mul_f32_e32 v24, 0xbfb8aa3b, v26
	v_mul_f32_e32 v25, 0xbfb8aa3b, v12
	v_exp_f32_e32 v24, v24
	v_exp_f32_e32 v25, v25
	s_nop 0
	v_pk_add_f32 v[24:25], v[24:25], 1.0 op_sel_hi:[1,0]
	s_nop 0
	s_nop 0
	v_rcp_f32_e32 v27, v25
	s_nop 0
	v_mul_f32_e32 v25, v12, v27
	s_nop 0
	v_rcp_f32_e32 v12, v24
	s_nop 0
	v_mul_f32_e32 v24, v26, v12
	v_lshlrev_b32_e32 v12, 16, v11
	v_lshlrev_b32_e32 v26, 16, v19
	v_and_b32_e32 v27, 0xffff0000, v19
	v_lshlrev_b32_e32 v28, 16, v15
	v_and_b32_e32 v29, 0xffff0000, v15
	v_and_b32_e32 v11, 0xffff0000, v11
	v_mul_f32_e32 v15, 0xbfb8aa3b, v12
	v_pk_add_f32 v[26:27], v[26:27], v[28:29]
	v_exp_f32_e32 v28, v15
	v_mul_f32_e32 v15, 0xbfb8aa3b, v11
	v_exp_f32_e32 v29, v15
	s_nop 0
	v_pk_add_f32 v[28:29], v[28:29], 1.0 op_sel_hi:[1,0]
	s_nop 0
	s_nop 0
	v_rcp_f32_e32 v15, v29
	s_nop 0
	v_mul_f32_e32 v29, v11, v15
	s_nop 0
	v_lshlrev_b32_e32 v30, 16, v18
	v_and_b32_e32 v31, 0xffff0000, v18
	v_lshlrev_b32_e32 v18, 16, v14
	v_and_b32_e32 v19, 0xffff0000, v14
	v_pk_add_f32 v[18:19], v[30:31], v[18:19]
	v_mov_b32_e32 v15, v26
	v_mov_b32_e32 v14, v18
	v_pk_mul_f32 v[14:15], v[14:15], v[14:15]
	v_mov_b32_e32 v30, v19
	v_mov_b32_e32 v31, v27
	v_rcp_f32_e32 v11, v28
	s_nop 0
	v_mul_f32_e32 v28, v12, v11
	v_pk_fma_f32 v[14:15], v[30:31], v[30:31], v[14:15]
	v_lshlrev_b32_e32 v12, 16, v10
	v_and_b32_e32 v30, 0xffff0000, v10
	v_mul_f32_e32 v10, 0xbfb8aa3b, v12
	v_mul_f32_e32 v11, 0xbfb8aa3b, v30
	v_exp_f32_e32 v10, v10
	v_exp_f32_e32 v11, v11
	s_nop 0
	v_pk_add_f32 v[10:11], v[10:11], 1.0 op_sel_hi:[1,0]
	s_nop 0
	s_nop 0
	v_rcp_f32_e32 v31, v11
	s_nop 0
	v_mul_f32_e32 v11, v30, v31
	s_nop 0
	v_rcp_f32_e32 v30, v10
	s_nop 0
	v_mul_f32_e32 v10, v12, v30
	v_add_f32_e32 v12, v14, v15
	v_add_f32_e32 v12, v21, v12
	v_add_f32_e32 v12, v20, v12
	s_waitcnt lgkmcnt(0)
	s_nop 1
	v_add_f32_dpp v12, v12, v12 quad_perm:[1,0,3,2] row_mask:0xf bank_mask:0xf
	s_waitcnt lgkmcnt(0)
	s_nop 1
	v_add_f32_dpp v12, v12, v12 quad_perm:[2,3,0,1] row_mask:0xf bank_mask:0xf
	s_waitcnt lgkmcnt(0)
	s_nop 1
	v_add_f32_dpp v12, v12, v12 row_half_mirror row_mask:0xf bank_mask:0xf
	s_waitcnt lgkmcnt(0)
	s_nop 1
	v_add_f32_dpp v12, v12, v12 row_mirror row_mask:0xf bank_mask:0xf
	v_fmamk_f32 v12, v12, 0x3c000000, v65
	v_cmp_gt_f32_e32 vcc, s5, v12
	v_mul_f32_e32 v14, 0x4f800000, v12
	s_nop 0
	v_cndmask_b32_e32 v12, v12, v14, vcc
	v_sqrt_f32_e32 v14, v12
	s_nop 0
	v_add_u32_e32 v15, -1, v14
	v_fma_f32 v20, -v15, v14, v12
	v_cmp_ge_f32_e64 s[0:1], 0, v20
	v_add_u32_e32 v20, 1, v14
	s_nop 0
	v_cndmask_b32_e64 v15, v14, v15, s[0:1]
	v_fma_f32 v14, -v20, v14, v12
	v_cmp_lt_f32_e64 s[0:1], 0, v14
	s_nop 1
	v_cndmask_b32_e64 v14, v15, v20, s[0:1]
	v_mul_f32_e32 v15, 0x37800000, v14
	v_cndmask_b32_e32 v14, v14, v15, vcc
	v_cmp_class_f32_e32 vcc, v12, v66
	s_nop 1
	v_cndmask_b32_e32 v12, v14, v12, vcc
	s_nop 0
	v_rcp_f32_e32 v14, v12
	s_nop 0
	v_pk_mul_f32 v[18:19], v[18:19], v[14:15] op_sel_hi:[1,0]
	v_pk_mul_f32 v[16:17], v[16:17], v[14:15] op_sel_hi:[1,0]
	v_pk_mul_f32 v[18:19], v[2:3], v[18:19]
	v_pk_mul_f32 v[16:17], v[6:7], v[16:17]
	v_pk_mul_f32 v[10:11], v[10:11], v[18:19]
	v_pk_mul_f32 v[18:19], v[26:27], v[14:15] op_sel_hi:[1,0]
	v_cvt_pk_bf16_f32 v10, v10, v11
	v_pk_mul_f32 v[18:19], v[4:5], v[18:19]
	v_pk_mul_f32 v[16:17], v[24:25], v[16:17]
	v_pk_mul_f32 v[18:19], v[28:29], v[18:19]
	v_cvt_pk_bf16_f32 v12, v16, v17
	v_cvt_pk_bf16_f32 v11, v18, v19
	v_lshlrev_b32_e32 v18, 16, v13
	v_and_b32_e32 v13, 0xffff0000, v13
	v_mul_f32_e32 v15, 0xbfb8aa3b, v18
	v_mul_f32_e32 v17, 0xbfb8aa3b, v13
	v_exp_f32_e32 v16, v15
	v_exp_f32_e32 v17, v17
	v_pk_mul_f32 v[14:15], v[22:23], v[14:15] op_sel_hi:[1,0]
	v_pk_add_f32 v[16:17], v[16:17], 1.0 op_sel_hi:[1,0]
	s_nop 0
	v_pk_mul_f32 v[14:15], v[8:9], v[14:15]
	v_rcp_f32_e32 v19, v17
	s_nop 0
	v_mul_f32_e32 v17, v13, v19
	s_nop 0
	v_rcp_f32_e32 v13, v16
	s_nop 0
	v_mul_f32_e32 v16, v18, v13
	v_pk_mul_f32 v[14:15], v[16:17], v[14:15]
	s_nop 0
	v_cvt_pk_bf16_f32 v13, v14, v15
	global_store_dwordx4 v[56:57], v[10:13], off offset:2048 sc1
	s_cbranch_scc1 .LBB0_311
